# F-phase residual epilogue: all 16 residual-tile loads issued up front into dead operand registers (SGPR-base addressing), waits recounted; on top of E+A deferred stores
# speedup vs baseline: 1.0051x; 1.0051x over previous
; #define PG8_STAGE(bufoff, gbase, voff) do { _Pragma("unroll") for (int _i = 0; _i < 2; ++_i) \
;         __builtin_amdgcn_global_load_lds((const unsigned*)((const char*)(gbase) + (voff)[_i]), (LAS unsigned*)(lds + (bufoff) + ldsw + _i * 8192), 16, 0, 0); } while (0)
; #define PG8_LDA(dst, b, h) do { _Pragma("unroll") for (int m = 0; m < 4; ++m) _Pragma("unroll") for (int k = 0; k < 2; ++k) dst[m][k] = *(const LAS bf16x8*)(lds + PG8_SA(b, h) + aoff + m * 2048 + k * 1024); } while (0)
; #define PG8_LDB(dst, b, h) do { _Pragma("unroll") for (int n = 0; n < 2; ++n) _Pragma("unroll") for (int k = 0; k < 2; ++k) dst[n][k] = *(const LAS bf16x8*)(lds + PG8_SB(b, h) + boff + n * 2048 + k * 1024); } while (0)
; #define PG8_MMA(ai, bj, At, Bt) do { __builtin_amdgcn_s_setprio(1); _Pragma("unroll") for (int m = 0; m < 4; ++m) _Pragma("unroll") for (int n = 0; n < 2; ++n) _Pragma("unroll") for (int k = 0; k < 2; ++k) \
;         acc[ai][bj][m][n] = __builtin_amdgcn_mfma_f32_16x16x32_bf16(Bt[n][k], At[m][k], acc[ai][bj][m][n], 0, 0, 0); __builtin_amdgcn_s_setprio(0); } while (0)
; #define PG8_WAIT_L(n) asm volatile("s_waitcnt lgkmcnt(" #n ")" ::: "memory")
; #define PG8_BAR __builtin_amdgcn_s_barrier()
; #define PG8_SCHED __builtin_amdgcn_sched_barrier(0)
; template <class Epi>
; __device__ __forceinline__ void gemm_phase(LAS unsigned char* lds, const Gemm g, const StaticOrder& S, const Epi& E) {
;     ...
;             const char* a2 = last ? nA : cA + (size_t)(t + 2) * kstep; const char* b2 = last ? nB : cB + (size_t)(t + 2) * kstep;
;             const char* a3 = a2 + kstep; const char* b3 = b2 + kstep;
;             PG8_LDB(B0, 0, 0); PG8_SCHED; PG8_LDA(At, 0, 0); PG8_STAGE(PG8_SA(1, 1), a1 + hstep, voffA);
;             PG8_WAIT_L(8); PG8_BAR; PG8_WAIT_L(0); PG8_MMA(0, 0, At, B0); PG8_BAR; PG8_SCHED;
;             PG8_LDB(B1, 0, 1); PG8_STAGE(PG8_SB(0, 0), b2, voffB);
;             PG8_BAR; PG8_WAIT_L(0); PG8_MMA(0, 1, At, B1); PG8_BAR;
;             PG8_LDA(At, 0, 1); PG8_STAGE(PG8_SA(0, 0), a2, voffA);
;             PG8_BAR; PG8_WAIT_L(0); PG8_MMA(1, 0, At, B0); PG8_BAR; PG8_SCHED;
.LBB0_103:
	s_add_u32 s5, s46, 0xfff00080
	s_addc_u32 s6, s47, -1
	s_add_i32 s58, 0, 0x10000
	v_add_u32_e32 v152, s58, v157
	ds_read_b128 v[130:133], v152
	ds_read_b128 v[134:137], v152 offset:1024
	ds_read_b128 v[148:151], v152 offset:2048
	ds_read_b128 v[152:155], v152 offset:3072
	s_cmp_eq_u32 s4, 60
	s_cselect_b32 s49, s25, s6
	s_cselect_b32 s48, s71, s5
	s_cselect_b32 s7, s13, vcc_hi
	s_cselect_b32 s6, s87, vcc_lo
	v_lshl_add_u64 v[162:163], s[46:47], 0, v[144:145]
	s_add_i32 m0, s92, 0xc000
	ds_read_b128 v[170:173], v168
	ds_read_b128 v[174:177], v168 offset:1024
	ds_read_b128 v[178:181], v168 offset:2048
	ds_read_b128 v[182:185], v168 offset:3072
	ds_read_b128 v[204:207], v168 offset:4096
	ds_read_b128 v[208:211], v168 offset:5120
	ds_read_b128 v[212:215], v168 offset:6144
	ds_read_b128 v[216:219], v168 offset:7168
	global_load_lds_dwordx4 v[162:163], off
	v_lshl_add_u64 v[162:163], s[46:47], 0, v[146:147]
	s_add_i32 m0, s92, 0xe000
	s_nop 0
	global_load_lds_dwordx4 v[162:163], off
	s_waitcnt lgkmcnt(8)
	s_barrier
	s_waitcnt lgkmcnt(0)
	s_setprio 1
	s_waitcnt lgkmcnt(0)
	v_mfma_f32_16x16x32_bf16 v[126:129], v[130:133], v[170:173], v[126:129]
	v_mfma_f32_16x16x32_bf16 v[122:125], v[148:151], v[170:173], v[122:125]
	v_mfma_f32_16x16x32_bf16 v[110:113], v[130:133], v[178:181], v[110:113]
	v_mfma_f32_16x16x32_bf16 v[106:109], v[148:151], v[178:181], v[106:109]
	v_mfma_f32_16x16x32_bf16 v[94:97], v[130:133], v[204:207], v[94:97]
	v_mfma_f32_16x16x32_bf16 v[90:93], v[148:151], v[204:207], v[90:93]
	v_mfma_f32_16x16x32_bf16 v[78:81], v[130:133], v[212:215], v[78:81]
	v_mfma_f32_16x16x32_bf16 v[74:77], v[148:151], v[212:215], v[74:77]
	v_mfma_f32_16x16x32_bf16 v[126:129], v[134:137], v[174:177], v[126:129]
	v_mfma_f32_16x16x32_bf16 v[122:125], v[152:155], v[174:177], v[122:125]
	v_mfma_f32_16x16x32_bf16 v[110:113], v[134:137], v[182:185], v[110:113]
	v_mfma_f32_16x16x32_bf16 v[106:109], v[152:155], v[182:185], v[106:109]
	v_mfma_f32_16x16x32_bf16 v[94:97], v[134:137], v[208:211], v[94:97]
	v_mfma_f32_16x16x32_bf16 v[90:93], v[152:155], v[208:211], v[90:93]
	v_mfma_f32_16x16x32_bf16 v[78:81], v[134:137], v[216:219], v[78:81]
	v_mfma_f32_16x16x32_bf16 v[74:77], v[152:155], v[216:219], v[74:77]
	s_setprio 0
	s_barrier
	s_add_i32 s5, 0, 0x14000
	v_add_u32_e32 v162, s5, v157
	s_add_i32 s58, s58, s91
	ds_read_b128 v[226:229], v162
	ds_read_b128 v[230:233], v162 offset:1024
	ds_read_b128 v[234:237], v162 offset:2048
	ds_read_b128 v[238:241], v162 offset:3072
	v_lshl_add_u64 v[162:163], s[6:7], 0, v[0:1]
	s_mov_b32 m0, s58
	v_lshl_add_u64 v[186:187], s[6:7], 0, v[138:139]
	global_load_lds_dwordx4 v[162:163], off
	s_add_i32 m0, s58, 0x2000
	s_nop 0
	global_load_lds_dwordx4 v[186:187], off
	s_barrier
	s_waitcnt lgkmcnt(0)
	s_setprio 1
	s_waitcnt lgkmcnt(0)
	v_mfma_f32_16x16x32_bf16 v[118:121], v[226:229], v[170:173], v[118:121]
	v_mfma_f32_16x16x32_bf16 v[114:117], v[234:237], v[170:173], v[114:117]
	v_mfma_f32_16x16x32_bf16 v[102:105], v[226:229], v[178:181], v[102:105]
	v_mfma_f32_16x16x32_bf16 v[98:101], v[234:237], v[178:181], v[98:101]
	v_mfma_f32_16x16x32_bf16 v[86:89], v[226:229], v[204:207], v[86:89]
	v_mfma_f32_16x16x32_bf16 v[82:85], v[234:237], v[204:207], v[82:85]
	v_mfma_f32_16x16x32_bf16 v[70:73], v[226:229], v[212:215], v[70:73]
	v_mfma_f32_16x16x32_bf16 v[66:69], v[234:237], v[212:215], v[66:69]
	v_mfma_f32_16x16x32_bf16 v[118:121], v[230:233], v[174:177], v[118:121]
	v_mfma_f32_16x16x32_bf16 v[114:117], v[238:241], v[174:177], v[114:117]
	v_mfma_f32_16x16x32_bf16 v[102:105], v[230:233], v[182:185], v[102:105]
	v_mfma_f32_16x16x32_bf16 v[98:101], v[238:241], v[182:185], v[98:101]
	v_mfma_f32_16x16x32_bf16 v[86:89], v[230:233], v[208:211], v[86:89]
	v_mfma_f32_16x16x32_bf16 v[82:85], v[238:241], v[208:211], v[82:85]
	v_mfma_f32_16x16x32_bf16 v[70:73], v[230:233], v[216:219], v[70:73]
	v_mfma_f32_16x16x32_bf16 v[66:69], v[238:241], v[216:219], v[66:69]
	s_setprio 0
	s_mov_b32 m0, s92
	v_lshl_add_u64 v[220:221], s[48:49], 0, v[142:143]
	s_barrier
	ds_read_b128 v[170:173], v168 offset:16384
	ds_read_b128 v[174:177], v168 offset:17408
	ds_read_b128 v[178:181], v168 offset:18432
	ds_read_b128 v[182:185], v168 offset:19456
	ds_read_b128 v[204:207], v168 offset:20480
	ds_read_b128 v[208:211], v168 offset:21504
	ds_read_b128 v[212:215], v168 offset:22528
	ds_read_b128 v[216:219], v168 offset:23552
	global_load_lds_dwordx4 v[220:221], off
	v_lshl_add_u64 v[242:243], s[48:49], 0, v[140:141]
	s_mov_b32 m0, s93
	s_nop 0
	global_load_lds_dwordx4 v[242:243], off
	s_barrier
	s_waitcnt lgkmcnt(0)
	s_setprio 1
	s_waitcnt lgkmcnt(0)
	v_mfma_f32_16x16x32_bf16 v[62:65], v[130:133], v[170:173], v[62:65]
	v_mfma_f32_16x16x32_bf16 v[58:61], v[148:151], v[170:173], v[58:61]
	v_mfma_f32_16x16x32_bf16 v[46:49], v[130:133], v[178:181], v[46:49]
	v_mfma_f32_16x16x32_bf16 v[42:45], v[148:151], v[178:181], v[42:45]
	v_mfma_f32_16x16x32_bf16 v[30:33], v[130:133], v[204:207], v[30:33]
	v_mfma_f32_16x16x32_bf16 v[26:29], v[148:151], v[204:207], v[26:29]
	v_mfma_f32_16x16x32_bf16 v[14:17], v[130:133], v[212:215], v[14:17]
	v_mfma_f32_16x16x32_bf16 v[10:13], v[148:151], v[212:215], v[10:13]
	v_mfma_f32_16x16x32_bf16 v[62:65], v[134:137], v[174:177], v[62:65]
	v_mfma_f32_16x16x32_bf16 v[58:61], v[152:155], v[174:177], v[58:61]
	v_mfma_f32_16x16x32_bf16 v[46:49], v[134:137], v[182:185], v[46:49]
	v_mfma_f32_16x16x32_bf16 v[42:45], v[152:155], v[182:185], v[42:45]
	v_mfma_f32_16x16x32_bf16 v[30:33], v[134:137], v[208:211], v[30:33]
	v_mfma_f32_16x16x32_bf16 v[26:29], v[152:155], v[208:211], v[26:29]
	v_mfma_f32_16x16x32_bf16 v[14:17], v[134:137], v[216:219], v[14:17]
	v_mfma_f32_16x16x32_bf16 v[10:13], v[152:155], v[216:219], v[10:13]
	s_setprio 0
	s_barrier
; #define PG8_STAGE(bufoff, gbase, voff) do { _Pragma("unroll") for (int _i = 0; _i < 2; ++_i) \
;         __builtin_amdgcn_global_load_lds((const unsigned*)((const char*)(gbase) + (voff)[_i]), (LAS unsigned*)(lds + (bufoff) + ldsw + _i * 8192), 16, 0, 0); } while (0)
; #define PG8_LDA(dst, b, h) do { _Pragma("unroll") for (int m = 0; m < 4; ++m) _Pragma("unroll") for (int k = 0; k < 2; ++k) dst[m][k] = *(const LAS bf16x8*)(lds + PG8_SA(b, h) + aoff + m * 2048 + k * 1024); } while (0)
; #define PG8_LDB(dst, b, h) do { _Pragma("unroll") for (int n = 0; n < 2; ++n) _Pragma("unroll") for (int k = 0; k < 2; ++k) dst[n][k] = *(const LAS bf16x8*)(lds + PG8_SB(b, h) + boff + n * 2048 + k * 1024); } while (0)
; #define PG8_WAIT_V(n) asm volatile("s_waitcnt vmcnt(" #n ")" ::: "memory")
; #define PG8_WAIT_L(n) asm volatile("s_waitcnt lgkmcnt(" #n ")" ::: "memory")
; #define PG8_BAR __builtin_amdgcn_s_barrier()
; #define PG8_SCHED __builtin_amdgcn_sched_barrier(0)
; template <class Epi>
; __device__ __forceinline__ void gemm_phase(LAS unsigned char* lds, const Gemm g, const StaticOrder& S, const Epi& E) {
;     ...
;             PG8_LDB(B0, 0, 0); PG8_SCHED; PG8_LDA(At, 0, 0); PG8_STAGE(PG8_SA(1, 1), a1 + hstep, voffA);
;             PG8_WAIT_L(8); PG8_BAR; PG8_WAIT_L(0); PG8_MMA(0, 0, At, B0); PG8_BAR; PG8_SCHED;
;             PG8_LDB(B1, 0, 1); PG8_STAGE(PG8_SB(0, 0), b2, voffB);
;             PG8_BAR; PG8_WAIT_L(0); PG8_MMA(0, 1, At, B1); PG8_BAR;
;             PG8_LDA(At, 0, 1); PG8_STAGE(PG8_SA(0, 0), a2, voffA);
;             PG8_BAR; PG8_WAIT_L(0); PG8_MMA(1, 0, At, B0); PG8_BAR; PG8_SCHED;
;             PG8_STAGE(PG8_SB(0, 1), b2 + hstep, voffB);
;             PG8_WAIT_V(6); PG8_BAR; PG8_MMA(1, 1, At, B1); PG8_BAR;
;             PG8_LDB(B0, 1, 0); PG8_SCHED; PG8_LDA(At, 1, 0); PG8_STAGE(PG8_SA(0, 1), a2 + hstep, voffA);
;             PG8_WAIT_L(8); PG8_BAR; PG8_WAIT_L(0); PG8_MMA(0, 0, At, B0); PG8_BAR; PG8_SCHED;
;             PG8_LDB(B1, 1, 1); PG8_STAGE(PG8_SB(1, 0), b3, voffB);
;             PG8_BAR; PG8_WAIT_L(0); PG8_MMA(0, 1, At, B1); PG8_BAR;
;             PG8_LDA(At, 1, 1); PG8_STAGE(PG8_SA(1, 0), a3, voffA);
;             PG8_BAR; PG8_WAIT_L(0); PG8_MMA(1, 0, At, B0); PG8_BAR; PG8_SCHED;
;             PG8_STAGE(PG8_SB(1, 1), b3 + hstep, voffB);
;             PG8_WAIT_V(6); PG8_BAR; PG8_MMA(1, 1, At, B1); PG8_BAR;
	s_add_u32 s60, s6, 0x100000
	s_addc_u32 s61, s7, 0
	s_add_i32 s5, s5, s91
	v_lshl_add_u64 v[130:131], s[60:61], 0, v[0:1]
	s_mov_b32 m0, s5
	s_nop 0
	global_load_lds_dwordx4 v[130:131], off
	v_lshl_add_u64 v[130:131], s[60:61], 0, v[138:139]
	s_add_i32 m0, s5, 0x2000
	s_nop 0
	global_load_lds_dwordx4 v[130:131], off
	s_waitcnt vmcnt(6)
	s_barrier
	s_setprio 1
	v_mfma_f32_16x16x32_bf16 v[54:57], v[226:229], v[170:173], v[54:57]
	v_mfma_f32_16x16x32_bf16 v[50:53], v[234:237], v[170:173], v[50:53]
	v_mfma_f32_16x16x32_bf16 v[38:41], v[226:229], v[178:181], v[38:41]
	v_mfma_f32_16x16x32_bf16 v[34:37], v[234:237], v[178:181], v[34:37]
	v_mfma_f32_16x16x32_bf16 v[22:25], v[226:229], v[204:207], v[22:25]
	v_mfma_f32_16x16x32_bf16 v[18:21], v[234:237], v[204:207], v[18:21]
	v_mfma_f32_16x16x32_bf16 v[6:9], v[226:229], v[212:215], v[6:9]
	v_mfma_f32_16x16x32_bf16 v[2:5], v[234:237], v[212:215], v[2:5]
	v_mfma_f32_16x16x32_bf16 v[54:57], v[230:233], v[174:177], v[54:57]
	v_mfma_f32_16x16x32_bf16 v[50:53], v[238:241], v[174:177], v[50:53]
	v_mfma_f32_16x16x32_bf16 v[38:41], v[230:233], v[182:185], v[38:41]
	v_mfma_f32_16x16x32_bf16 v[34:37], v[238:241], v[182:185], v[34:37]
	v_mfma_f32_16x16x32_bf16 v[22:25], v[230:233], v[208:211], v[22:25]
	v_mfma_f32_16x16x32_bf16 v[18:21], v[238:241], v[208:211], v[18:21]
	v_mfma_f32_16x16x32_bf16 v[6:9], v[230:233], v[216:219], v[6:9]
	v_mfma_f32_16x16x32_bf16 v[2:5], v[238:241], v[216:219], v[2:5]
	s_setprio 0
	s_add_i32 s5, 0, 0x18000
	v_add_u32_e32 v152, s5, v157
	s_barrier
	ds_read_b128 v[130:133], v152
	ds_read_b128 v[134:137], v152 offset:1024
	ds_read_b128 v[148:151], v152 offset:2048
	ds_read_b128 v[152:155], v152 offset:3072
	s_add_u32 s48, s48, 0x100000
	s_addc_u32 s49, s49, 0
	s_mov_b32 m0, s96
	v_lshl_add_u64 v[226:227], s[48:49], 0, v[142:143]
	ds_read_b128 v[170:173], v168 offset:32768
	ds_read_b128 v[174:177], v168 offset:33792
	ds_read_b128 v[178:181], v168 offset:34816
	ds_read_b128 v[182:185], v168 offset:35840
	ds_read_b128 v[204:207], v168 offset:36864
	ds_read_b128 v[208:211], v168 offset:37888
	ds_read_b128 v[212:215], v168 offset:38912
	ds_read_b128 v[216:219], v168 offset:39936
	global_load_lds_dwordx4 v[226:227], off
	v_lshl_add_u64 v[226:227], s[48:49], 0, v[140:141]
	s_mov_b32 m0, s97
	s_nop 0
	global_load_lds_dwordx4 v[226:227], off
	s_waitcnt lgkmcnt(8)
	s_barrier
	s_waitcnt lgkmcnt(0)
	s_setprio 1
	s_waitcnt lgkmcnt(0)
	v_mfma_f32_16x16x32_bf16 v[126:129], v[130:133], v[170:173], v[126:129]
	v_mfma_f32_16x16x32_bf16 v[122:125], v[148:151], v[170:173], v[122:125]
	v_mfma_f32_16x16x32_bf16 v[110:113], v[130:133], v[178:181], v[110:113]
	v_mfma_f32_16x16x32_bf16 v[106:109], v[148:151], v[178:181], v[106:109]
	v_mfma_f32_16x16x32_bf16 v[94:97], v[130:133], v[204:207], v[94:97]
	v_mfma_f32_16x16x32_bf16 v[90:93], v[148:151], v[204:207], v[90:93]
	v_mfma_f32_16x16x32_bf16 v[78:81], v[130:133], v[212:215], v[78:81]
	v_mfma_f32_16x16x32_bf16 v[74:77], v[148:151], v[212:215], v[74:77]
	v_mfma_f32_16x16x32_bf16 v[126:129], v[134:137], v[174:177], v[126:129]
	v_mfma_f32_16x16x32_bf16 v[122:125], v[152:155], v[174:177], v[122:125]
	v_mfma_f32_16x16x32_bf16 v[110:113], v[134:137], v[182:185], v[110:113]
	v_mfma_f32_16x16x32_bf16 v[106:109], v[152:155], v[182:185], v[106:109]
	v_mfma_f32_16x16x32_bf16 v[94:97], v[134:137], v[208:211], v[94:97]
	v_mfma_f32_16x16x32_bf16 v[90:93], v[152:155], v[208:211], v[90:93]
	v_mfma_f32_16x16x32_bf16 v[78:81], v[134:137], v[216:219], v[78:81]
	v_mfma_f32_16x16x32_bf16 v[74:77], v[152:155], v[216:219], v[74:77]
	s_setprio 0
	s_barrier
	s_add_i32 s48, 0, 0x1c000
	s_add_i32 s5, s5, s91
	v_add_u32_e32 v169, s48, v157
	v_lshl_add_u64 v[162:163], v[162:163], 0, s[26:27]
	s_mov_b32 m0, s5
	ds_read_b128 v[226:229], v169
	ds_read_b128 v[230:233], v169 offset:1024
	ds_read_b128 v[234:237], v169 offset:2048
	ds_read_b128 v[238:241], v169 offset:3072
	global_load_lds_dwordx4 v[162:163], off
	v_lshl_add_u64 v[162:163], v[186:187], 0, s[26:27]
	s_add_i32 m0, s5, 0x2000
	s_nop 0
	global_load_lds_dwordx4 v[162:163], off
	s_barrier
	s_waitcnt lgkmcnt(0)
	s_setprio 1
	s_waitcnt lgkmcnt(0)
	v_mfma_f32_16x16x32_bf16 v[118:121], v[226:229], v[170:173], v[118:121]
	v_mfma_f32_16x16x32_bf16 v[114:117], v[234:237], v[170:173], v[114:117]
	v_mfma_f32_16x16x32_bf16 v[102:105], v[226:229], v[178:181], v[102:105]
	v_mfma_f32_16x16x32_bf16 v[98:101], v[234:237], v[178:181], v[98:101]
	v_mfma_f32_16x16x32_bf16 v[86:89], v[226:229], v[204:207], v[86:89]
	v_mfma_f32_16x16x32_bf16 v[82:85], v[234:237], v[204:207], v[82:85]
	v_mfma_f32_16x16x32_bf16 v[70:73], v[226:229], v[212:215], v[70:73]
	v_mfma_f32_16x16x32_bf16 v[66:69], v[234:237], v[212:215], v[66:69]
	v_mfma_f32_16x16x32_bf16 v[118:121], v[230:233], v[174:177], v[118:121]
	v_mfma_f32_16x16x32_bf16 v[114:117], v[238:241], v[174:177], v[114:117]
	v_mfma_f32_16x16x32_bf16 v[102:105], v[230:233], v[182:185], v[102:105]
	v_mfma_f32_16x16x32_bf16 v[98:101], v[238:241], v[182:185], v[98:101]
	v_mfma_f32_16x16x32_bf16 v[86:89], v[230:233], v[208:211], v[86:89]
	v_mfma_f32_16x16x32_bf16 v[82:85], v[238:241], v[208:211], v[82:85]
	v_mfma_f32_16x16x32_bf16 v[70:73], v[230:233], v[216:219], v[70:73]
	v_mfma_f32_16x16x32_bf16 v[66:69], v[238:241], v[216:219], v[66:69]
	s_setprio 0
	s_mov_b32 m0, s54
	v_lshl_add_u64 v[162:163], v[220:221], 0, s[26:27]
	s_barrier
	ds_read_b128 v[170:173], v168 offset:49152
	ds_read_b128 v[174:177], v168 offset:50176
	ds_read_b128 v[178:181], v168 offset:51200
	ds_read_b128 v[182:185], v168 offset:52224
	ds_read_b128 v[204:207], v168 offset:53248
	ds_read_b128 v[208:211], v168 offset:54272
	ds_read_b128 v[212:215], v168 offset:55296
	ds_read_b128 v[216:219], v168 offset:56320
	global_load_lds_dwordx4 v[162:163], off
	v_lshl_add_u64 v[162:163], v[242:243], 0, s[26:27]
	s_mov_b32 m0, s84
	s_nop 0
	global_load_lds_dwordx4 v[162:163], off
	s_barrier
; #define PG8_STAGE(bufoff, gbase, voff) do { _Pragma("unroll") for (int _i = 0; _i < 2; ++_i) \
;         __builtin_amdgcn_global_load_lds((const unsigned*)((const char*)(gbase) + (voff)[_i]), (LAS unsigned*)(lds + (bufoff) + ldsw + _i * 8192), 16, 0, 0); } while (0)
; #define PG8_LDA(dst, b, h) do { _Pragma("unroll") for (int m = 0; m < 4; ++m) _Pragma("unroll") for (int k = 0; k < 2; ++k) dst[m][k] = *(const LAS bf16x8*)(lds + PG8_SA(b, h) + aoff + m * 2048 + k * 1024); } while (0)
; #define PG8_WAIT_V(n) asm volatile("s_waitcnt vmcnt(" #n ")" ::: "memory")
; #define PG8_WAIT_L(n) asm volatile("s_waitcnt lgkmcnt(" #n ")" ::: "memory")
; #define PG8_BAR __builtin_amdgcn_s_barrier()
;     __device__ __forceinline__ void operator()(const f32x4 (&acc)[2][2][4][2], const Unit& u, int  , int wr, int wc, int fr, int fq) const {
;         const int row0 = u.pm * BM + wr * 64 + fr, col0 = u.pn * BM + wc * 32 + 8 * fq;
;         u32x4 rv[2][2];
; #pragma unroll
;         for (int bj = 0; bj < 2; ++bj) rv[0][bj] = *(const u32x4*)(hb + (size_t)row0 * DM + col0 + bj * HALF);
; #pragma unroll
;         for (int g = 0; g < 8; ++g) {
;             const int ai = g >> 2, m = g & 3;
;             const int row = row0 + ai * HALF + m * 16; const size_t off = (size_t)row * DM + col0; float s = 0.f;
;             if (g < 7) { const int g1 = g + 1; const size_t off1 = (size_t)(row0 + (g1 >> 2) * HALF + (g1 & 3) * 16) * DM + col0;
; #pragma unroll
;                 for (int bj = 0; bj < 2; ++bj) rv[g1 & 1][bj] = *(const u32x4*)(hb + off1 + bj * HALF); }
; template <class Epi>
; __device__ __forceinline__ void gemm_phase(LAS unsigned char* lds, const Gemm g, const StaticOrder& S, const Epi& E) {
;     ...
;             PG8_WAIT_V(6); PG8_BAR; PG8_MMA(1, 1, At, B1); PG8_BAR;
;             PG8_LDB(B0, 1, 0); PG8_SCHED; PG8_LDA(At, 1, 0); PG8_STAGE(PG8_SA(0, 1), a2 + hstep, voffA);
;             PG8_WAIT_L(8); PG8_BAR; PG8_WAIT_L(0); PG8_MMA(0, 0, At, B0); PG8_BAR; PG8_SCHED;
;             PG8_LDB(B1, 1, 1); PG8_STAGE(PG8_SB(1, 0), b3, voffB);
;             PG8_BAR; PG8_WAIT_L(0); PG8_MMA(0, 1, At, B1); PG8_BAR;
;             PG8_LDA(At, 1, 1); PG8_STAGE(PG8_SA(1, 0), a3, voffA);
;             PG8_BAR; PG8_WAIT_L(0); PG8_MMA(1, 0, At, B0); PG8_BAR; PG8_SCHED;
;             PG8_STAGE(PG8_SB(1, 1), b3 + hstep, voffB);
;             PG8_WAIT_V(6); PG8_BAR; PG8_MMA(1, 1, At, B1); PG8_BAR;
	s_waitcnt lgkmcnt(0)
	s_setprio 1
	s_waitcnt lgkmcnt(0)
	v_mfma_f32_16x16x32_bf16 v[62:65], v[130:133], v[170:173], v[62:65]
	v_mfma_f32_16x16x32_bf16 v[58:61], v[148:151], v[170:173], v[58:61]
	v_mfma_f32_16x16x32_bf16 v[46:49], v[130:133], v[178:181], v[46:49]
	v_mfma_f32_16x16x32_bf16 v[42:45], v[148:151], v[178:181], v[42:45]
	v_mfma_f32_16x16x32_bf16 v[30:33], v[130:133], v[204:207], v[30:33]
	v_mfma_f32_16x16x32_bf16 v[26:29], v[148:151], v[204:207], v[26:29]
	v_mfma_f32_16x16x32_bf16 v[14:17], v[130:133], v[212:215], v[14:17]
	v_mfma_f32_16x16x32_bf16 v[10:13], v[148:151], v[212:215], v[10:13]
	v_mfma_f32_16x16x32_bf16 v[62:65], v[134:137], v[174:177], v[62:65]
	v_mfma_f32_16x16x32_bf16 v[58:61], v[152:155], v[174:177], v[58:61]
	v_mfma_f32_16x16x32_bf16 v[46:49], v[134:137], v[182:185], v[46:49]
	v_mfma_f32_16x16x32_bf16 v[42:45], v[152:155], v[182:185], v[42:45]
	v_mfma_f32_16x16x32_bf16 v[30:33], v[134:137], v[208:211], v[30:33]
	v_mfma_f32_16x16x32_bf16 v[26:29], v[152:155], v[208:211], v[26:29]
	v_mfma_f32_16x16x32_bf16 v[14:17], v[134:137], v[216:219], v[14:17]
	v_mfma_f32_16x16x32_bf16 v[10:13], v[152:155], v[216:219], v[10:13]
	s_setprio 0
	s_barrier
	s_add_u32 s6, s6, 0x100080
	s_addc_u32 s7, s7, 0
	s_add_i32 s5, s48, s91
	v_lshl_add_u64 v[130:131], s[6:7], 0, v[0:1]
	s_mov_b32 m0, s5
	s_nop 0
	global_load_lds_dwordx4 v[130:131], off
	v_lshl_add_u64 v[130:131], s[6:7], 0, v[138:139]
	s_add_i32 m0, s5, 0x2000
	s_nop 0
	global_load_lds_dwordx4 v[130:131], off
	s_waitcnt vmcnt(6)
	s_barrier
	s_setprio 1
	v_mfma_f32_16x16x32_bf16 v[54:57], v[226:229], v[170:173], v[54:57]
	v_mfma_f32_16x16x32_bf16 v[50:53], v[234:237], v[170:173], v[50:53]
	v_mfma_f32_16x16x32_bf16 v[38:41], v[226:229], v[178:181], v[38:41]
	v_mfma_f32_16x16x32_bf16 v[34:37], v[234:237], v[178:181], v[34:37]
	v_mfma_f32_16x16x32_bf16 v[22:25], v[226:229], v[204:207], v[22:25]
	v_mfma_f32_16x16x32_bf16 v[18:21], v[234:237], v[204:207], v[18:21]
	v_mfma_f32_16x16x32_bf16 v[6:9], v[226:229], v[212:215], v[6:9]
	v_mfma_f32_16x16x32_bf16 v[2:5], v[234:237], v[212:215], v[2:5]
	v_mfma_f32_16x16x32_bf16 v[54:57], v[230:233], v[174:177], v[54:57]
	v_mfma_f32_16x16x32_bf16 v[50:53], v[238:241], v[174:177], v[50:53]
	v_mfma_f32_16x16x32_bf16 v[38:41], v[230:233], v[182:185], v[38:41]
	v_mfma_f32_16x16x32_bf16 v[34:37], v[238:241], v[182:185], v[34:37]
	v_mfma_f32_16x16x32_bf16 v[22:25], v[230:233], v[208:211], v[22:25]
	v_mfma_f32_16x16x32_bf16 v[18:21], v[238:241], v[208:211], v[18:21]
	v_mfma_f32_16x16x32_bf16 v[6:9], v[230:233], v[216:219], v[6:9]
	v_mfma_f32_16x16x32_bf16 v[2:5], v[238:241], v[216:219], v[2:5]
	s_setprio 0
	s_add_i32 s4, s4, 2
	s_add_u32 s46, s46, 0x100
	s_addc_u32 s47, s47, 0
	s_add_u32 vcc_lo, vcc_lo, 0x100
	s_addc_u32 vcc_hi, vcc_hi, 0
	s_cmp_gt_u32 s4, 61
	s_barrier
	s_cbranch_scc0 .LBB0_103
	v_lshl_add_u32 v150, s86, 8, v156
	v_lshl_or_b32 v148, s18, 8, v166
	v_ashrrev_i32_e32 v151, 31, v150
	v_lshlrev_b64 v[130:131], 11, v[150:151]
	v_ashrrev_i32_e32 v149, 31, v148
	v_lshl_add_u64 v[130:131], s[8:9], 0, v[130:131]
	v_lshlrev_b64 v[132:133], 1, v[148:149]
	v_lshl_add_u64 v[162:163], v[130:131], 0, v[132:133]
	global_load_dwordx4 v[170:173], v[162:163], off
	global_load_dwordx4 v[174:177], v[162:163], off offset:256
	v_or_b32_e32 v152, 16, v150
	v_ashrrev_i32_e32 v153, 31, v152
	v_lshlrev_b64 v[130:131], 11, v[152:153]
	v_lshl_add_u64 v[130:131], s[8:9], 0, v[130:131]
	v_lshl_add_u64 v[154:155], v[130:131], 0, v[132:133]
	global_load_dwordx4 v[134:137], v[154:155], off
	global_load_dwordx4 v[130:133], v[154:155], off offset:256
	v_lshlrev_b32_e32 v202, 11, v150
	v_lshl_add_u32 v202, v148, 1, v202
	v_add_u32_e32 v202, 0x10000, v202
	global_load_dwordx4 v[204:207], v202, s[8:9]
	global_load_dwordx4 v[208:211], v202, s[8:9] offset:256
	v_add_u32_e32 v202, 0x8000, v202
	global_load_dwordx4 v[212:215], v202, s[8:9]
	global_load_dwordx4 v[216:219], v202, s[8:9] offset:256
	v_add_u32_e32 v202, 0x28000, v202
	global_load_dwordx4 v[226:229], v202, s[8:9]
	global_load_dwordx4 v[230:233], v202, s[8:9] offset:256
	v_add_u32_e32 v202, 0x8000, v202
	global_load_dwordx4 v[234:237], v202, s[8:9]
	global_load_dwordx4 v[238:241], v202, s[8:9] offset:256
	v_add_u32_e32 v202, 0x8000, v202
	global_load_dwordx4 v[158:161], v202, s[8:9]
	global_load_dwordx4 v[188:191], v202, s[8:9] offset:256
	v_add_u32_e32 v202, 0x8000, v202
	global_load_dwordx4 v[194:197], v202, s[8:9]
	global_load_dwordx4 v[198:201], v202, s[8:9] offset:256
	v_and_b32_e32 v178, 64, v193
	v_xor_b32_e32 v169, 16, v193
	s_lshl_b32 s6, s18, 2
	s_ashr_i32 s7, s6, 31
	s_waitcnt vmcnt(12)
; __device__ __forceinline__ unsigned pk2(float lo, float hi) { unsigned r; asm("v_cvt_pk_bf16_f32 %0, %1, %2" : "=v"(r) : "v"(lo), "v"(hi)); return r; }
; __device__ __forceinline__ float bf_lo(unsigned w) { return __uint_as_float(w << 16); }
; __device__ __forceinline__ float bf_hi(unsigned w) { return __uint_as_float(w & 0xffff0000u); }
;     __device__ __forceinline__ void operator()(const f32x4 (&acc)[2][2][4][2], const Unit& u, int  , int wr, int wc, int fr, int fq) const {
;     ...
;         for (int g = 0; g < 8; ++g) {
;             const int ai = g >> 2, m = g & 3;
;             const int row = row0 + ai * HALF + m * 16; const size_t off = (size_t)row * DM + col0; float s = 0.f;
;             if (g < 7) { const int g1 = g + 1; const size_t off1 = (size_t)(row0 + (g1 >> 2) * HALF + (g1 & 3) * 16) * DM + col0;
; #pragma unroll
;                 for (int bj = 0; bj < 2; ++bj) rv[g1 & 1][bj] = *(const u32x4*)(hb + off1 + bj * HALF); }
; #pragma unroll
;             for (int bj = 0; bj < 2; ++bj) {
;                 const u32x4 r = rv[g & 1][bj]; const f32x4 a0 = acc[ai][bj][m][0], a1 = acc[ai][bj][m][1];
;                 u32x4 o; o.x = pk2(bf_lo(r.x) + a0[0], bf_hi(r.x) + a0[1]); o.y = pk2(bf_lo(r.y) + a0[2], bf_hi(r.y) + a0[3]);
;                 o.z = pk2(bf_lo(r.z) + a1[0], bf_hi(r.z) + a1[1]); o.w = pk2(bf_lo(r.w) + a1[2], bf_hi(r.w) + a1[3]);
;                 *(u32x4*)(hb + off + bj * HALF) = o;
; #pragma unroll
;                 for (int e = 0; e < 4; ++e) { const float x0 = bf_lo(o[e]), x1 = bf_hi(o[e]); s += x0 * x0 + x1 * x1; }
;             }
;             s += __shfl_xor(s, 16); s += __shfl_xor(s, 32);
;             if (fq == 0) ssq[(size_t)row * 16 + u.pn * 4 + wc] = s;
	v_lshlrev_b32_e32 v181, 16, v172
	v_lshlrev_b32_e32 v182, 16, v173
	v_and_b32_e32 v173, 0xffff0000, v173
	v_lshlrev_b32_e32 v185, 16, v176
	v_and_b32_e32 v176, 0xffff0000, v176
	v_lshlrev_b32_e32 v179, 16, v170
	v_and_b32_e32 v170, 0xffff0000, v170
	v_lshlrev_b32_e32 v180, 16, v171
	v_and_b32_e32 v171, 0xffff0000, v171
	v_and_b32_e32 v172, 0xffff0000, v172
	v_lshlrev_b32_e32 v183, 16, v174
	v_and_b32_e32 v174, 0xffff0000, v174
	v_lshlrev_b32_e32 v186, 16, v177
	v_and_b32_e32 v177, 0xffff0000, v177
	v_add_f32_e32 v122, v122, v181
	v_add_f32_e32 v125, v125, v173
	v_add_f32_e32 v115, v115, v176
	v_add_f32_e32 v126, v126, v179
	v_add_f32_e32 v127, v127, v170
	v_add_f32_e32 v128, v128, v180
	v_add_f32_e32 v129, v129, v171
	v_add_f32_e32 v123, v123, v172
	v_add_f32_e32 v124, v124, v182
	v_add_f32_e32 v170, v118, v183
	v_add_f32_e32 v171, v119, v174
	v_add_f32_e32 v114, v114, v185
	v_add_f32_e32 v173, v116, v186
	v_add_f32_e32 v174, v117, v177
	v_cvt_pk_bf16_f32 v116, v126, v127
	v_cvt_pk_bf16_f32 v117, v128, v129
	v_cvt_pk_bf16_f32 v118, v122, v123
	v_cvt_pk_bf16_f32 v119, v124, v125
	v_cvt_pk_bf16_f32 v122, v114, v115
	v_lshlrev_b32_e32 v184, 16, v175
	v_and_b32_e32 v115, 0xffff0000, v116
	v_and_b32_e32 v125, 0xffff0000, v117
	v_lshlrev_b32_e32 v114, 16, v116
	v_lshlrev_b32_e32 v124, 16, v117
	v_and_b32_e32 v127, 0xffff0000, v118
	v_mul_f32_e32 v115, v115, v115
	v_mul_f32_e32 v125, v125, v125
	v_and_b32_e32 v175, 0xffff0000, v175
	v_lshlrev_b32_e32 v126, 16, v118
	v_and_b32_e32 v129, 0xffff0000, v119
	v_mul_f32_e32 v127, v127, v127
	v_fmac_f32_e32 v115, v114, v114
	v_fmac_f32_e32 v125, v124, v124
	v_add_f32_e32 v172, v120, v184
	v_add_f32_e32 v121, v121, v175
	v_cvt_pk_bf16_f32 v120, v170, v171
	v_lshlrev_b32_e32 v128, 16, v119
	v_and_b32_e32 v171, 0xffff0000, v120
	v_mul_f32_e32 v129, v129, v129
	v_fmac_f32_e32 v127, v126, v126
	v_add_f32_e32 v114, v115, v125
	v_cvt_pk_bf16_f32 v121, v172, v121
	v_cvt_pk_bf16_f32 v123, v173, v174
	v_lshlrev_b32_e32 v170, 16, v120
	v_and_b32_e32 v173, 0xffff0000, v121
	v_mul_f32_e32 v171, v171, v171
	v_fmac_f32_e32 v129, v128, v128
	v_add_f32_e32 v114, v114, v127
	v_lshlrev_b32_e32 v172, 16, v121
	v_and_b32_e32 v175, 0xffff0000, v122
	v_mul_f32_e32 v173, v173, v173
	v_fmac_f32_e32 v171, v170, v170
	v_add_f32_e32 v114, v114, v129
	v_lshlrev_b32_e32 v174, 16, v122
	v_and_b32_e32 v177, 0xffff0000, v123
	v_mul_f32_e32 v175, v175, v175
	v_fmac_f32_e32 v173, v172, v172
	v_add_f32_e32 v114, v114, v171
	v_add_u32_e32 v115, 64, v178
	v_lshlrev_b32_e32 v176, 16, v123
	v_mul_f32_e32 v177, v177, v177
	v_fmac_f32_e32 v175, v174, v174
	v_add_f32_e32 v114, v114, v173
	v_cmp_lt_i32_e32 vcc, v169, v115
	v_fmac_f32_e32 v177, v176, v176
	v_add_f32_e32 v114, v114, v175
	v_cndmask_b32_e32 v124, v193, v169, vcc
	v_add_f32_e32 v114, v114, v177
	v_lshlrev_b32_e32 v126, 2, v124
	ds_bpermute_b32 v124, v126, v114
	global_store_dwordx4 v[162:163], v[116:119], off
	global_store_dwordx4 v[162:163], v[120:123], off offset:256
	s_waitcnt lgkmcnt(0)
	v_add_f32_e32 v114, v114, v124
	v_xor_b32_e32 v124, 32, v193
	v_cmp_lt_i32_e32 vcc, v124, v115
	s_nop 1
	v_cndmask_b32_e32 v115, v193, v124, vcc
	v_lshlrev_b32_e32 v127, 2, v115
	ds_bpermute_b32 v115, v127, v114
	s_and_saveexec_b64 s[46:47], s[40:41]
	s_cbranch_execz .LBB0_106
	s_waitcnt lgkmcnt(0)
	v_add_f32_e32 v116, v114, v115
	v_lshlrev_b64 v[114:115], 6, v[150:151]
	v_lshl_add_u64 v[114:115], s[10:11], 0, v[114:115]
	v_lshl_add_u64 v[114:115], s[6:7], 2, v[114:115]
	s_lshl_b32 s18, s83, 2
	v_lshl_add_u64 v[114:115], v[114:115], 0, s[18:19]
	global_store_dword v[114:115], v116, off
.LBB0_106:
	s_or_b64 exec, exec, s[46:47]
	v_or_b32_e32 v122, 32, v150
	v_ashrrev_i32_e32 v123, 31, v122
	s_waitcnt lgkmcnt(0)
	v_lshlrev_b64 v[114:115], 11, v[122:123]
	v_lshl_add_u64 v[114:115], s[8:9], 0, v[114:115]
	v_lshl_add_u64 v[124:125], v[148:149], 1, v[114:115]
	v_lshlrev_b32_e32 v128, 16, v134
	v_add_f32_e32 v110, v110, v128
	v_and_b32_e32 v128, 0xffff0000, v134
	v_add_f32_e32 v111, v111, v128
	v_cvt_pk_bf16_f32 v110, v110, v111
	v_lshlrev_b32_e32 v111, 16, v135
	v_add_f32_e32 v111, v112, v111
	v_and_b32_e32 v112, 0xffff0000, v135
	v_add_f32_e32 v112, v113, v112
	v_cvt_pk_bf16_f32 v111, v111, v112
	v_lshlrev_b32_e32 v112, 16, v136
	v_add_f32_e32 v106, v106, v112
	v_and_b32_e32 v112, 0xffff0000, v136
	v_add_f32_e32 v107, v107, v112
	v_cvt_pk_bf16_f32 v112, v106, v107
	v_and_b32_e32 v107, 0xffff0000, v137
	v_lshlrev_b32_e32 v106, 16, v137
	v_add_f32_e32 v107, v109, v107
	v_add_f32_e32 v106, v108, v106
	v_cvt_pk_bf16_f32 v113, v106, v107
	v_and_b32_e32 v107, 0xffff0000, v110
	v_lshlrev_b32_e32 v106, 16, v110
	v_mul_f32_e32 v107, v107, v107
	v_and_b32_e32 v108, 0xffff0000, v111
	v_fmac_f32_e32 v107, v106, v106
	v_lshlrev_b32_e32 v106, 16, v111
	v_mul_f32_e32 v108, v108, v108
	v_fmac_f32_e32 v108, v106, v106
	v_add_f32_e32 v106, v107, v108
	v_and_b32_e32 v108, 0xffff0000, v112
	v_lshlrev_b32_e32 v107, 16, v112
	v_mul_f32_e32 v108, v108, v108
	v_fmac_f32_e32 v108, v107, v107
	v_add_f32_e32 v106, v106, v108
	v_and_b32_e32 v108, 0xffff0000, v113
	v_lshlrev_b32_e32 v107, 16, v113
	v_mul_f32_e32 v108, v108, v108
	v_fmac_f32_e32 v108, v107, v107
	v_lshlrev_b32_e32 v107, 16, v130
	v_add_f32_e32 v102, v102, v107
	v_and_b32_e32 v107, 0xffff0000, v130
	v_add_f32_e32 v103, v103, v107
	v_cvt_pk_bf16_f32 v102, v102, v103
	v_lshlrev_b32_e32 v103, 16, v131
	v_add_f32_e32 v103, v104, v103
	v_and_b32_e32 v104, 0xffff0000, v131
	v_add_f32_e32 v104, v105, v104
	v_cvt_pk_bf16_f32 v103, v103, v104
	v_lshlrev_b32_e32 v104, 16, v132
	v_add_f32_e32 v98, v98, v104
	v_and_b32_e32 v104, 0xffff0000, v132
	v_add_f32_e32 v99, v99, v104
	v_cvt_pk_bf16_f32 v104, v98, v99
	v_and_b32_e32 v99, 0xffff0000, v133
	v_lshlrev_b32_e32 v98, 16, v133
	v_add_f32_e32 v99, v101, v99
	v_add_f32_e32 v98, v100, v98
	v_cvt_pk_bf16_f32 v105, v98, v99
	v_and_b32_e32 v99, 0xffff0000, v102
	v_lshlrev_b32_e32 v98, 16, v102
	v_mul_f32_e32 v99, v99, v99
	v_add_f32_e32 v106, v106, v108
	v_fmac_f32_e32 v99, v98, v98
	v_and_b32_e32 v100, 0xffff0000, v103
	v_add_f32_e32 v98, v106, v99
	v_lshlrev_b32_e32 v99, 16, v103
	v_mul_f32_e32 v100, v100, v100
	v_fmac_f32_e32 v100, v99, v99
	v_add_f32_e32 v98, v98, v100
	v_and_b32_e32 v100, 0xffff0000, v104
	v_lshlrev_b32_e32 v99, 16, v104
	v_mul_f32_e32 v100, v100, v100
	v_fmac_f32_e32 v100, v99, v99
	v_add_f32_e32 v98, v98, v100
	v_and_b32_e32 v100, 0xffff0000, v105
	v_lshlrev_b32_e32 v99, 16, v105
	v_mul_f32_e32 v100, v100, v100
	v_fmac_f32_e32 v100, v99, v99
	v_add_f32_e32 v98, v98, v100
	ds_bpermute_b32 v99, v126, v98
	global_store_dwordx4 v[154:155], v[110:113], off
	global_store_dwordx4 v[154:155], v[102:105], off offset:256
	s_waitcnt lgkmcnt(0)
	v_add_f32_e32 v98, v98, v99
	ds_bpermute_b32 v99, v127, v98
	s_and_saveexec_b64 s[46:47], s[40:41]
	s_cbranch_execz .LBB0_108
; __device__ __forceinline__ unsigned pk2(float lo, float hi) { unsigned r; asm("v_cvt_pk_bf16_f32 %0, %1, %2" : "=v"(r) : "v"(lo), "v"(hi)); return r; }
; __device__ __forceinline__ float bf_lo(unsigned w) { return __uint_as_float(w << 16); }
; __device__ __forceinline__ float bf_hi(unsigned w) { return __uint_as_float(w & 0xffff0000u); }
;     __device__ __forceinline__ void operator()(const f32x4 (&acc)[2][2][4][2], const Unit& u, int  , int wr, int wc, int fr, int fq) const {
;     ...
;         for (int g = 0; g < 8; ++g) {
;             const int ai = g >> 2, m = g & 3;
;             const int row = row0 + ai * HALF + m * 16; const size_t off = (size_t)row * DM + col0; float s = 0.f;
;             if (g < 7) { const int g1 = g + 1; const size_t off1 = (size_t)(row0 + (g1 >> 2) * HALF + (g1 & 3) * 16) * DM + col0;
; #pragma unroll
;                 for (int bj = 0; bj < 2; ++bj) rv[g1 & 1][bj] = *(const u32x4*)(hb + off1 + bj * HALF); }
; #pragma unroll
;             for (int bj = 0; bj < 2; ++bj) {
;                 const u32x4 r = rv[g & 1][bj]; const f32x4 a0 = acc[ai][bj][m][0], a1 = acc[ai][bj][m][1];
;                 u32x4 o; o.x = pk2(bf_lo(r.x) + a0[0], bf_hi(r.x) + a0[1]); o.y = pk2(bf_lo(r.y) + a0[2], bf_hi(r.y) + a0[3]);
;                 o.z = pk2(bf_lo(r.z) + a1[0], bf_hi(r.z) + a1[1]); o.w = pk2(bf_lo(r.w) + a1[2], bf_hi(r.w) + a1[3]);
;                 *(u32x4*)(hb + off + bj * HALF) = o;
; #pragma unroll
;                 for (int e = 0; e < 4; ++e) { const float x0 = bf_lo(o[e]), x1 = bf_hi(o[e]); s += x0 * x0 + x1 * x1; }
;             }
;             s += __shfl_xor(s, 16); s += __shfl_xor(s, 32);
;             if (fq == 0) ssq[(size_t)row * 16 + u.pn * 4 + wc] = s;
	s_waitcnt lgkmcnt(0)
	v_add_f32_e32 v100, v98, v99
	v_lshlrev_b64 v[98:99], 6, v[152:153]
	v_lshl_add_u64 v[98:99], s[10:11], 0, v[98:99]
	v_lshl_add_u64 v[98:99], s[6:7], 2, v[98:99]
	s_lshl_b32 s18, s83, 2
	v_lshl_add_u64 v[98:99], v[98:99], 0, s[18:19]
	global_store_dword v[98:99], v100, off
.LBB0_108:
	s_or_b64 exec, exec, s[46:47]
	v_or_b32_e32 v106, 48, v150
	v_ashrrev_i32_e32 v107, 31, v106
	s_waitcnt lgkmcnt(0)
	v_lshlrev_b64 v[98:99], 11, v[106:107]
	v_lshl_add_u64 v[98:99], s[8:9], 0, v[98:99]
	v_lshl_add_u64 v[108:109], v[148:149], 1, v[98:99]
	s_waitcnt vmcnt(15)
	v_lshlrev_b32_e32 v110, 16, v204
	v_add_f32_e32 v94, v94, v110
	v_and_b32_e32 v110, 0xffff0000, v204
	v_add_f32_e32 v95, v95, v110
	v_cvt_pk_bf16_f32 v94, v94, v95
	v_lshlrev_b32_e32 v95, 16, v205
	v_add_f32_e32 v95, v96, v95
	v_and_b32_e32 v96, 0xffff0000, v205
	v_add_f32_e32 v96, v97, v96
	v_cvt_pk_bf16_f32 v95, v95, v96
	v_lshlrev_b32_e32 v96, 16, v206
	v_add_f32_e32 v90, v90, v96
	v_and_b32_e32 v96, 0xffff0000, v206
	v_add_f32_e32 v91, v91, v96
	v_cvt_pk_bf16_f32 v96, v90, v91
	v_and_b32_e32 v91, 0xffff0000, v207
	v_lshlrev_b32_e32 v90, 16, v207
	v_add_f32_e32 v91, v93, v91
	v_add_f32_e32 v90, v92, v90
	v_cvt_pk_bf16_f32 v97, v90, v91
	v_and_b32_e32 v91, 0xffff0000, v94
	v_lshlrev_b32_e32 v90, 16, v94
	v_mul_f32_e32 v91, v91, v91
	v_and_b32_e32 v92, 0xffff0000, v95
	v_fmac_f32_e32 v91, v90, v90
	v_lshlrev_b32_e32 v90, 16, v95
	v_mul_f32_e32 v92, v92, v92
	v_fmac_f32_e32 v92, v90, v90
	v_add_f32_e32 v90, v91, v92
	v_and_b32_e32 v92, 0xffff0000, v96
	v_lshlrev_b32_e32 v91, 16, v96
	v_mul_f32_e32 v92, v92, v92
	v_fmac_f32_e32 v92, v91, v91
	v_add_f32_e32 v90, v90, v92
	v_and_b32_e32 v92, 0xffff0000, v97
	v_lshlrev_b32_e32 v91, 16, v97
	v_mul_f32_e32 v92, v92, v92
	v_fmac_f32_e32 v92, v91, v91
	s_waitcnt vmcnt(14)
	v_lshlrev_b32_e32 v91, 16, v208
	v_add_f32_e32 v86, v86, v91
	v_and_b32_e32 v91, 0xffff0000, v208
	v_add_f32_e32 v87, v87, v91
	v_cvt_pk_bf16_f32 v86, v86, v87
	v_lshlrev_b32_e32 v87, 16, v209
	v_add_f32_e32 v87, v88, v87
	v_and_b32_e32 v88, 0xffff0000, v209
	v_add_f32_e32 v88, v89, v88
	v_cvt_pk_bf16_f32 v87, v87, v88
	v_lshlrev_b32_e32 v88, 16, v210
	v_add_f32_e32 v82, v82, v88
	v_and_b32_e32 v88, 0xffff0000, v210
	v_add_f32_e32 v83, v83, v88
	v_cvt_pk_bf16_f32 v88, v82, v83
	v_and_b32_e32 v83, 0xffff0000, v211
	v_lshlrev_b32_e32 v82, 16, v211
	v_add_f32_e32 v83, v85, v83
	v_add_f32_e32 v82, v84, v82
	v_cvt_pk_bf16_f32 v89, v82, v83
	v_and_b32_e32 v83, 0xffff0000, v86
	v_lshlrev_b32_e32 v82, 16, v86
	v_mul_f32_e32 v83, v83, v83
	v_add_f32_e32 v90, v90, v92
	v_fmac_f32_e32 v83, v82, v82
	v_and_b32_e32 v84, 0xffff0000, v87
	v_add_f32_e32 v82, v90, v83
	v_lshlrev_b32_e32 v83, 16, v87
	v_mul_f32_e32 v84, v84, v84
	v_fmac_f32_e32 v84, v83, v83
	v_add_f32_e32 v82, v82, v84
	v_and_b32_e32 v84, 0xffff0000, v88
	v_lshlrev_b32_e32 v83, 16, v88
	v_mul_f32_e32 v84, v84, v84
	v_fmac_f32_e32 v84, v83, v83
	v_add_f32_e32 v82, v82, v84
	v_and_b32_e32 v84, 0xffff0000, v89
	v_lshlrev_b32_e32 v83, 16, v89
	v_mul_f32_e32 v84, v84, v84
	v_fmac_f32_e32 v84, v83, v83
	v_add_f32_e32 v82, v82, v84
	ds_bpermute_b32 v83, v126, v82
	global_store_dwordx4 v[124:125], v[94:97], off
	global_store_dwordx4 v[124:125], v[86:89], off offset:256
	s_waitcnt lgkmcnt(0)
	v_add_f32_e32 v82, v82, v83
	ds_bpermute_b32 v83, v127, v82
	s_and_saveexec_b64 s[46:47], s[40:41]
	s_cbranch_execz .LBB0_110
	s_waitcnt lgkmcnt(0)
	v_add_f32_e32 v84, v82, v83
	v_lshlrev_b64 v[82:83], 6, v[122:123]
	v_lshl_add_u64 v[82:83], s[10:11], 0, v[82:83]
	v_lshl_add_u64 v[82:83], s[6:7], 2, v[82:83]
	s_lshl_b32 s18, s83, 2
	v_lshl_add_u64 v[82:83], v[82:83], 0, s[18:19]
	global_store_dword v[82:83], v84, off
.LBB0_110:
	s_or_b64 exec, exec, s[46:47]
	v_add_u32_e32 v90, 0x80, v150
	v_ashrrev_i32_e32 v91, 31, v90
	s_waitcnt lgkmcnt(0)
	v_lshlrev_b64 v[82:83], 11, v[90:91]
	v_lshl_add_u64 v[82:83], s[8:9], 0, v[82:83]
	v_lshl_add_u64 v[92:93], v[148:149], 1, v[82:83]
	s_waitcnt vmcnt(15)
	v_lshlrev_b32_e32 v94, 16, v212
	v_add_f32_e32 v78, v78, v94
	v_and_b32_e32 v94, 0xffff0000, v212
	v_add_f32_e32 v79, v79, v94
	v_cvt_pk_bf16_f32 v78, v78, v79
	v_lshlrev_b32_e32 v79, 16, v213
	v_add_f32_e32 v79, v80, v79
	v_and_b32_e32 v80, 0xffff0000, v213
	v_add_f32_e32 v80, v81, v80
	v_cvt_pk_bf16_f32 v79, v79, v80
	v_lshlrev_b32_e32 v80, 16, v214
	v_add_f32_e32 v74, v74, v80
	v_and_b32_e32 v80, 0xffff0000, v214
	v_add_f32_e32 v75, v75, v80
	v_cvt_pk_bf16_f32 v80, v74, v75
	v_and_b32_e32 v75, 0xffff0000, v215
	v_lshlrev_b32_e32 v74, 16, v215
	v_add_f32_e32 v75, v77, v75
	v_add_f32_e32 v74, v76, v74
	v_cvt_pk_bf16_f32 v81, v74, v75
	v_and_b32_e32 v75, 0xffff0000, v78
	v_lshlrev_b32_e32 v74, 16, v78
	v_mul_f32_e32 v75, v75, v75
	v_and_b32_e32 v76, 0xffff0000, v79
	v_fmac_f32_e32 v75, v74, v74
	v_lshlrev_b32_e32 v74, 16, v79
	v_mul_f32_e32 v76, v76, v76
	v_fmac_f32_e32 v76, v74, v74
	v_add_f32_e32 v74, v75, v76
	v_and_b32_e32 v76, 0xffff0000, v80
	v_lshlrev_b32_e32 v75, 16, v80
	v_mul_f32_e32 v76, v76, v76
	v_fmac_f32_e32 v76, v75, v75
	v_add_f32_e32 v74, v74, v76
	v_and_b32_e32 v76, 0xffff0000, v81
	v_lshlrev_b32_e32 v75, 16, v81
	v_mul_f32_e32 v76, v76, v76
	v_fmac_f32_e32 v76, v75, v75
	s_waitcnt vmcnt(14)
	v_lshlrev_b32_e32 v75, 16, v216
	v_add_f32_e32 v70, v70, v75
	v_and_b32_e32 v75, 0xffff0000, v216
	v_add_f32_e32 v71, v71, v75
	v_cvt_pk_bf16_f32 v70, v70, v71
	v_lshlrev_b32_e32 v71, 16, v217
	v_add_f32_e32 v71, v72, v71
	v_and_b32_e32 v72, 0xffff0000, v217
	v_add_f32_e32 v72, v73, v72
	v_cvt_pk_bf16_f32 v71, v71, v72
	v_lshlrev_b32_e32 v72, 16, v218
	v_add_f32_e32 v66, v66, v72
	v_and_b32_e32 v72, 0xffff0000, v218
	v_add_f32_e32 v67, v67, v72
	v_cvt_pk_bf16_f32 v72, v66, v67
	v_and_b32_e32 v67, 0xffff0000, v219
	v_lshlrev_b32_e32 v66, 16, v219
	v_add_f32_e32 v67, v69, v67
	v_add_f32_e32 v66, v68, v66
	v_cvt_pk_bf16_f32 v73, v66, v67
	v_and_b32_e32 v67, 0xffff0000, v70
	v_lshlrev_b32_e32 v66, 16, v70
	v_mul_f32_e32 v67, v67, v67
	v_add_f32_e32 v74, v74, v76
	v_fmac_f32_e32 v67, v66, v66
	v_and_b32_e32 v68, 0xffff0000, v71
	v_add_f32_e32 v66, v74, v67
	v_lshlrev_b32_e32 v67, 16, v71
	v_mul_f32_e32 v68, v68, v68
	v_fmac_f32_e32 v68, v67, v67
	v_add_f32_e32 v66, v66, v68
	v_and_b32_e32 v68, 0xffff0000, v72
	v_lshlrev_b32_e32 v67, 16, v72
	v_mul_f32_e32 v68, v68, v68
	v_fmac_f32_e32 v68, v67, v67
	v_add_f32_e32 v66, v66, v68
	v_and_b32_e32 v68, 0xffff0000, v73
	v_lshlrev_b32_e32 v67, 16, v73
	v_mul_f32_e32 v68, v68, v68
	v_fmac_f32_e32 v68, v67, v67
	v_add_f32_e32 v66, v66, v68
	ds_bpermute_b32 v67, v126, v66
	global_store_dwordx4 v[108:109], v[78:81], off
	global_store_dwordx4 v[108:109], v[70:73], off offset:256
	s_waitcnt lgkmcnt(0)
	v_add_f32_e32 v66, v66, v67
	ds_bpermute_b32 v67, v127, v66
	s_and_saveexec_b64 s[46:47], s[40:41]
	s_cbranch_execz .LBB0_112
; __device__ __forceinline__ unsigned pk2(float lo, float hi) { unsigned r; asm("v_cvt_pk_bf16_f32 %0, %1, %2" : "=v"(r) : "v"(lo), "v"(hi)); return r; }
; __device__ __forceinline__ float bf_lo(unsigned w) { return __uint_as_float(w << 16); }
; __device__ __forceinline__ float bf_hi(unsigned w) { return __uint_as_float(w & 0xffff0000u); }
;     __device__ __forceinline__ void operator()(const f32x4 (&acc)[2][2][4][2], const Unit& u, int  , int wr, int wc, int fr, int fq) const {
;     ...
;         for (int g = 0; g < 8; ++g) {
;             const int ai = g >> 2, m = g & 3;
;             const int row = row0 + ai * HALF + m * 16; const size_t off = (size_t)row * DM + col0; float s = 0.f;
;             if (g < 7) { const int g1 = g + 1; const size_t off1 = (size_t)(row0 + (g1 >> 2) * HALF + (g1 & 3) * 16) * DM + col0;
; #pragma unroll
;                 for (int bj = 0; bj < 2; ++bj) rv[g1 & 1][bj] = *(const u32x4*)(hb + off1 + bj * HALF); }
; #pragma unroll
;             for (int bj = 0; bj < 2; ++bj) {
;                 const u32x4 r = rv[g & 1][bj]; const f32x4 a0 = acc[ai][bj][m][0], a1 = acc[ai][bj][m][1];
;                 u32x4 o; o.x = pk2(bf_lo(r.x) + a0[0], bf_hi(r.x) + a0[1]); o.y = pk2(bf_lo(r.y) + a0[2], bf_hi(r.y) + a0[3]);
;                 o.z = pk2(bf_lo(r.z) + a1[0], bf_hi(r.z) + a1[1]); o.w = pk2(bf_lo(r.w) + a1[2], bf_hi(r.w) + a1[3]);
;                 *(u32x4*)(hb + off + bj * HALF) = o;
; #pragma unroll
;                 for (int e = 0; e < 4; ++e) { const float x0 = bf_lo(o[e]), x1 = bf_hi(o[e]); s += x0 * x0 + x1 * x1; }
;             }
;             s += __shfl_xor(s, 16); s += __shfl_xor(s, 32);
;             if (fq == 0) ssq[(size_t)row * 16 + u.pn * 4 + wc] = s;
	s_waitcnt lgkmcnt(0)
	v_add_f32_e32 v68, v66, v67
	v_lshlrev_b64 v[66:67], 6, v[106:107]
	v_lshl_add_u64 v[66:67], s[10:11], 0, v[66:67]
	v_lshl_add_u64 v[66:67], s[6:7], 2, v[66:67]
	s_lshl_b32 s18, s83, 2
	v_lshl_add_u64 v[66:67], v[66:67], 0, s[18:19]
	global_store_dword v[66:67], v68, off
.LBB0_112:
	s_or_b64 exec, exec, s[46:47]
	v_or_b32_e32 v74, 16, v90
	v_ashrrev_i32_e32 v75, 31, v74
	s_waitcnt lgkmcnt(0)
	v_lshlrev_b64 v[66:67], 11, v[74:75]
	v_lshl_add_u64 v[66:67], s[8:9], 0, v[66:67]
	v_lshl_add_u64 v[76:77], v[148:149], 1, v[66:67]
	s_waitcnt vmcnt(15)
	v_lshlrev_b32_e32 v78, 16, v226
	v_add_f32_e32 v62, v62, v78
	v_and_b32_e32 v78, 0xffff0000, v226
	v_add_f32_e32 v63, v63, v78
	v_cvt_pk_bf16_f32 v62, v62, v63
	v_lshlrev_b32_e32 v63, 16, v227
	v_add_f32_e32 v63, v64, v63
	v_and_b32_e32 v64, 0xffff0000, v227
	v_add_f32_e32 v64, v65, v64
	v_cvt_pk_bf16_f32 v63, v63, v64
	v_lshlrev_b32_e32 v64, 16, v228
	v_add_f32_e32 v58, v58, v64
	v_and_b32_e32 v64, 0xffff0000, v228
	v_add_f32_e32 v59, v59, v64
	v_cvt_pk_bf16_f32 v64, v58, v59
	v_and_b32_e32 v59, 0xffff0000, v229
	v_lshlrev_b32_e32 v58, 16, v229
	v_add_f32_e32 v59, v61, v59
	v_add_f32_e32 v58, v60, v58
	v_cvt_pk_bf16_f32 v65, v58, v59
	v_and_b32_e32 v59, 0xffff0000, v62
	v_lshlrev_b32_e32 v58, 16, v62
	v_mul_f32_e32 v59, v59, v59
	v_and_b32_e32 v60, 0xffff0000, v63
	v_fmac_f32_e32 v59, v58, v58
	v_lshlrev_b32_e32 v58, 16, v63
	v_mul_f32_e32 v60, v60, v60
	v_fmac_f32_e32 v60, v58, v58
	v_add_f32_e32 v58, v59, v60
	v_and_b32_e32 v60, 0xffff0000, v64
	v_lshlrev_b32_e32 v59, 16, v64
	v_mul_f32_e32 v60, v60, v60
	v_fmac_f32_e32 v60, v59, v59
	v_add_f32_e32 v58, v58, v60
	v_and_b32_e32 v60, 0xffff0000, v65
	v_lshlrev_b32_e32 v59, 16, v65
	v_mul_f32_e32 v60, v60, v60
	v_fmac_f32_e32 v60, v59, v59
	s_waitcnt vmcnt(14)
	v_lshlrev_b32_e32 v59, 16, v230
	v_add_f32_e32 v54, v54, v59
	v_and_b32_e32 v59, 0xffff0000, v230
	v_add_f32_e32 v55, v55, v59
	v_cvt_pk_bf16_f32 v54, v54, v55
	v_lshlrev_b32_e32 v55, 16, v231
	v_add_f32_e32 v55, v56, v55
	v_and_b32_e32 v56, 0xffff0000, v231
	v_add_f32_e32 v56, v57, v56
	v_cvt_pk_bf16_f32 v55, v55, v56
	v_lshlrev_b32_e32 v56, 16, v232
	v_add_f32_e32 v50, v50, v56
	v_and_b32_e32 v56, 0xffff0000, v232
	v_add_f32_e32 v51, v51, v56
	v_cvt_pk_bf16_f32 v56, v50, v51
	v_and_b32_e32 v51, 0xffff0000, v233
	v_lshlrev_b32_e32 v50, 16, v233
	v_add_f32_e32 v51, v53, v51
	v_add_f32_e32 v50, v52, v50
	v_cvt_pk_bf16_f32 v57, v50, v51
	v_and_b32_e32 v51, 0xffff0000, v54
	v_lshlrev_b32_e32 v50, 16, v54
	v_mul_f32_e32 v51, v51, v51
	v_add_f32_e32 v58, v58, v60
	v_fmac_f32_e32 v51, v50, v50
	v_and_b32_e32 v52, 0xffff0000, v55
	v_add_f32_e32 v50, v58, v51
	v_lshlrev_b32_e32 v51, 16, v55
	v_mul_f32_e32 v52, v52, v52
	v_fmac_f32_e32 v52, v51, v51
	v_add_f32_e32 v50, v50, v52
	v_and_b32_e32 v52, 0xffff0000, v56
	v_lshlrev_b32_e32 v51, 16, v56
	v_mul_f32_e32 v52, v52, v52
	v_fmac_f32_e32 v52, v51, v51
	v_add_f32_e32 v50, v50, v52
	v_and_b32_e32 v52, 0xffff0000, v57
	v_lshlrev_b32_e32 v51, 16, v57
	v_mul_f32_e32 v52, v52, v52
	v_fmac_f32_e32 v52, v51, v51
	v_add_f32_e32 v50, v50, v52
	ds_bpermute_b32 v51, v126, v50
	global_store_dwordx4 v[92:93], v[62:65], off
	global_store_dwordx4 v[92:93], v[54:57], off offset:256
	s_waitcnt lgkmcnt(0)
	v_add_f32_e32 v50, v50, v51
	ds_bpermute_b32 v51, v127, v50
	s_and_saveexec_b64 s[46:47], s[40:41]
	s_cbranch_execz .LBB0_114
	s_waitcnt lgkmcnt(0)
	v_add_f32_e32 v52, v50, v51
	v_lshlrev_b64 v[50:51], 6, v[90:91]
	v_lshl_add_u64 v[50:51], s[10:11], 0, v[50:51]
	v_lshl_add_u64 v[50:51], s[6:7], 2, v[50:51]
	s_lshl_b32 s18, s83, 2
	v_lshl_add_u64 v[50:51], v[50:51], 0, s[18:19]
	global_store_dword v[50:51], v52, off
.LBB0_114:
	s_or_b64 exec, exec, s[46:47]
	v_or_b32_e32 v58, 32, v90
	v_ashrrev_i32_e32 v59, 31, v58
	s_waitcnt lgkmcnt(0)
	v_lshlrev_b64 v[50:51], 11, v[58:59]
	v_lshl_add_u64 v[50:51], s[8:9], 0, v[50:51]
	v_lshl_add_u64 v[60:61], v[148:149], 1, v[50:51]
	s_waitcnt vmcnt(15)
	v_lshlrev_b32_e32 v62, 16, v234
	v_add_f32_e32 v46, v46, v62
	v_and_b32_e32 v62, 0xffff0000, v234
	v_add_f32_e32 v47, v47, v62
	v_cvt_pk_bf16_f32 v46, v46, v47
	v_lshlrev_b32_e32 v47, 16, v235
	v_add_f32_e32 v47, v48, v47
	v_and_b32_e32 v48, 0xffff0000, v235
	v_add_f32_e32 v48, v49, v48
	v_cvt_pk_bf16_f32 v47, v47, v48
	v_lshlrev_b32_e32 v48, 16, v236
	v_add_f32_e32 v42, v42, v48
	v_and_b32_e32 v48, 0xffff0000, v236
	v_add_f32_e32 v43, v43, v48
	v_cvt_pk_bf16_f32 v48, v42, v43
	v_and_b32_e32 v43, 0xffff0000, v237
	v_lshlrev_b32_e32 v42, 16, v237
	v_add_f32_e32 v43, v45, v43
	v_add_f32_e32 v42, v44, v42
	v_cvt_pk_bf16_f32 v49, v42, v43
	v_and_b32_e32 v43, 0xffff0000, v46
	v_lshlrev_b32_e32 v42, 16, v46
	v_mul_f32_e32 v43, v43, v43
	v_and_b32_e32 v44, 0xffff0000, v47
	v_fmac_f32_e32 v43, v42, v42
	v_lshlrev_b32_e32 v42, 16, v47
	v_mul_f32_e32 v44, v44, v44
	v_fmac_f32_e32 v44, v42, v42
	v_add_f32_e32 v42, v43, v44
	v_and_b32_e32 v44, 0xffff0000, v48
	v_lshlrev_b32_e32 v43, 16, v48
	v_mul_f32_e32 v44, v44, v44
	v_fmac_f32_e32 v44, v43, v43
	v_add_f32_e32 v42, v42, v44
	v_and_b32_e32 v44, 0xffff0000, v49
	v_lshlrev_b32_e32 v43, 16, v49
	v_mul_f32_e32 v44, v44, v44
	v_fmac_f32_e32 v44, v43, v43
	s_waitcnt vmcnt(14)
	v_lshlrev_b32_e32 v43, 16, v238
	v_add_f32_e32 v38, v38, v43
	v_and_b32_e32 v43, 0xffff0000, v238
	v_add_f32_e32 v39, v39, v43
	v_cvt_pk_bf16_f32 v38, v38, v39
	v_lshlrev_b32_e32 v39, 16, v239
	v_add_f32_e32 v39, v40, v39
	v_and_b32_e32 v40, 0xffff0000, v239
	v_add_f32_e32 v40, v41, v40
	v_cvt_pk_bf16_f32 v39, v39, v40
	v_lshlrev_b32_e32 v40, 16, v240
	v_add_f32_e32 v34, v34, v40
	v_and_b32_e32 v40, 0xffff0000, v240
	v_add_f32_e32 v35, v35, v40
	v_cvt_pk_bf16_f32 v40, v34, v35
	v_and_b32_e32 v35, 0xffff0000, v241
	v_lshlrev_b32_e32 v34, 16, v241
	v_add_f32_e32 v35, v37, v35
	v_add_f32_e32 v34, v36, v34
	v_cvt_pk_bf16_f32 v41, v34, v35
	v_and_b32_e32 v35, 0xffff0000, v38
	v_lshlrev_b32_e32 v34, 16, v38
	v_mul_f32_e32 v35, v35, v35
	v_add_f32_e32 v42, v42, v44
	v_fmac_f32_e32 v35, v34, v34
	v_and_b32_e32 v36, 0xffff0000, v39
	v_add_f32_e32 v34, v42, v35
	v_lshlrev_b32_e32 v35, 16, v39
	v_mul_f32_e32 v36, v36, v36
	v_fmac_f32_e32 v36, v35, v35
	v_add_f32_e32 v34, v34, v36
	v_and_b32_e32 v36, 0xffff0000, v40
	v_lshlrev_b32_e32 v35, 16, v40
	v_mul_f32_e32 v36, v36, v36
	v_fmac_f32_e32 v36, v35, v35
	v_add_f32_e32 v34, v34, v36
	v_and_b32_e32 v36, 0xffff0000, v41
	v_lshlrev_b32_e32 v35, 16, v41
	v_mul_f32_e32 v36, v36, v36
	v_fmac_f32_e32 v36, v35, v35
	v_add_f32_e32 v34, v34, v36
	ds_bpermute_b32 v35, v126, v34
	global_store_dwordx4 v[76:77], v[46:49], off
	global_store_dwordx4 v[76:77], v[38:41], off offset:256
	s_waitcnt lgkmcnt(0)
	v_add_f32_e32 v34, v34, v35
	ds_bpermute_b32 v35, v127, v34
	s_and_saveexec_b64 s[46:47], s[40:41]
	s_cbranch_execz .LBB0_116
; __device__ __forceinline__ unsigned pk2(float lo, float hi) { unsigned r; asm("v_cvt_pk_bf16_f32 %0, %1, %2" : "=v"(r) : "v"(lo), "v"(hi)); return r; }
; __device__ __forceinline__ float bf_lo(unsigned w) { return __uint_as_float(w << 16); }
; __device__ __forceinline__ float bf_hi(unsigned w) { return __uint_as_float(w & 0xffff0000u); }
;     __device__ __forceinline__ void operator()(const f32x4 (&acc)[2][2][4][2], const Unit& u, int  , int wr, int wc, int fr, int fq) const {
;     ...
;         for (int g = 0; g < 8; ++g) {
;             const int ai = g >> 2, m = g & 3;
;             const int row = row0 + ai * HALF + m * 16; const size_t off = (size_t)row * DM + col0; float s = 0.f;
;             if (g < 7) { const int g1 = g + 1; const size_t off1 = (size_t)(row0 + (g1 >> 2) * HALF + (g1 & 3) * 16) * DM + col0;
; #pragma unroll
;                 for (int bj = 0; bj < 2; ++bj) rv[g1 & 1][bj] = *(const u32x4*)(hb + off1 + bj * HALF); }
; #pragma unroll
;             for (int bj = 0; bj < 2; ++bj) {
;                 const u32x4 r = rv[g & 1][bj]; const f32x4 a0 = acc[ai][bj][m][0], a1 = acc[ai][bj][m][1];
;                 u32x4 o; o.x = pk2(bf_lo(r.x) + a0[0], bf_hi(r.x) + a0[1]); o.y = pk2(bf_lo(r.y) + a0[2], bf_hi(r.y) + a0[3]);
;                 o.z = pk2(bf_lo(r.z) + a1[0], bf_hi(r.z) + a1[1]); o.w = pk2(bf_lo(r.w) + a1[2], bf_hi(r.w) + a1[3]);
;                 *(u32x4*)(hb + off + bj * HALF) = o;
; #pragma unroll
;                 for (int e = 0; e < 4; ++e) { const float x0 = bf_lo(o[e]), x1 = bf_hi(o[e]); s += x0 * x0 + x1 * x1; }
;             }
;             s += __shfl_xor(s, 16); s += __shfl_xor(s, 32);
;             if (fq == 0) ssq[(size_t)row * 16 + u.pn * 4 + wc] = s;
	s_waitcnt lgkmcnt(0)
	v_add_f32_e32 v36, v34, v35
	v_lshlrev_b64 v[34:35], 6, v[74:75]
	v_lshl_add_u64 v[34:35], s[10:11], 0, v[34:35]
	v_lshl_add_u64 v[34:35], s[6:7], 2, v[34:35]
	s_lshl_b32 s18, s83, 2
	v_lshl_add_u64 v[34:35], v[34:35], 0, s[18:19]
	global_store_dword v[34:35], v36, off
.LBB0_116:
	s_or_b64 exec, exec, s[46:47]
	v_or_b32_e32 v42, 48, v90
	v_ashrrev_i32_e32 v43, 31, v42
	s_waitcnt lgkmcnt(0)
	v_lshlrev_b64 v[34:35], 11, v[42:43]
	v_lshl_add_u64 v[34:35], s[8:9], 0, v[34:35]
	v_lshl_add_u64 v[44:45], v[148:149], 1, v[34:35]
	s_waitcnt vmcnt(15)
	v_lshlrev_b32_e32 v46, 16, v158
	v_add_f32_e32 v30, v30, v46
	v_and_b32_e32 v46, 0xffff0000, v158
	v_add_f32_e32 v31, v31, v46
	v_cvt_pk_bf16_f32 v30, v30, v31
	v_lshlrev_b32_e32 v31, 16, v159
	v_add_f32_e32 v31, v32, v31
	v_and_b32_e32 v32, 0xffff0000, v159
	v_add_f32_e32 v32, v33, v32
	v_cvt_pk_bf16_f32 v31, v31, v32
	v_lshlrev_b32_e32 v32, 16, v160
	v_add_f32_e32 v26, v26, v32
	v_and_b32_e32 v32, 0xffff0000, v160
	v_add_f32_e32 v27, v27, v32
	v_cvt_pk_bf16_f32 v32, v26, v27
	v_and_b32_e32 v27, 0xffff0000, v161
	v_lshlrev_b32_e32 v26, 16, v161
	v_add_f32_e32 v27, v29, v27
	v_add_f32_e32 v26, v28, v26
	v_cvt_pk_bf16_f32 v33, v26, v27
	v_and_b32_e32 v27, 0xffff0000, v30
	v_lshlrev_b32_e32 v26, 16, v30
	v_mul_f32_e32 v27, v27, v27
	v_and_b32_e32 v28, 0xffff0000, v31
	v_fmac_f32_e32 v27, v26, v26
	v_lshlrev_b32_e32 v26, 16, v31
	v_mul_f32_e32 v28, v28, v28
	v_fmac_f32_e32 v28, v26, v26
	v_add_f32_e32 v26, v27, v28
	v_and_b32_e32 v28, 0xffff0000, v32
	v_lshlrev_b32_e32 v27, 16, v32
	v_mul_f32_e32 v28, v28, v28
	v_fmac_f32_e32 v28, v27, v27
	v_add_f32_e32 v26, v26, v28
	v_and_b32_e32 v28, 0xffff0000, v33
	v_lshlrev_b32_e32 v27, 16, v33
	v_mul_f32_e32 v28, v28, v28
	v_fmac_f32_e32 v28, v27, v27
	s_waitcnt vmcnt(14)
	v_lshlrev_b32_e32 v27, 16, v188
	v_add_f32_e32 v22, v22, v27
	v_and_b32_e32 v27, 0xffff0000, v188
	v_add_f32_e32 v23, v23, v27
	v_cvt_pk_bf16_f32 v22, v22, v23
	v_lshlrev_b32_e32 v23, 16, v189
	v_add_f32_e32 v23, v24, v23
	v_and_b32_e32 v24, 0xffff0000, v189
	v_add_f32_e32 v24, v25, v24
	v_cvt_pk_bf16_f32 v23, v23, v24
	v_lshlrev_b32_e32 v24, 16, v190
	v_add_f32_e32 v18, v18, v24
	v_and_b32_e32 v24, 0xffff0000, v190
	v_add_f32_e32 v19, v19, v24
	v_cvt_pk_bf16_f32 v24, v18, v19
	v_and_b32_e32 v19, 0xffff0000, v191
	v_lshlrev_b32_e32 v18, 16, v191
	v_add_f32_e32 v19, v21, v19
	v_add_f32_e32 v18, v20, v18
	v_cvt_pk_bf16_f32 v25, v18, v19
	v_and_b32_e32 v19, 0xffff0000, v22
	v_lshlrev_b32_e32 v18, 16, v22
	v_mul_f32_e32 v19, v19, v19
	v_add_f32_e32 v26, v26, v28
	v_fmac_f32_e32 v19, v18, v18
	v_and_b32_e32 v20, 0xffff0000, v23
	v_add_f32_e32 v18, v26, v19
	v_lshlrev_b32_e32 v19, 16, v23
	v_mul_f32_e32 v20, v20, v20
	v_fmac_f32_e32 v20, v19, v19
	v_add_f32_e32 v18, v18, v20
	v_and_b32_e32 v20, 0xffff0000, v24
	v_lshlrev_b32_e32 v19, 16, v24
	v_mul_f32_e32 v20, v20, v20
	v_fmac_f32_e32 v20, v19, v19
	v_add_f32_e32 v18, v18, v20
	v_and_b32_e32 v20, 0xffff0000, v25
	v_lshlrev_b32_e32 v19, 16, v25
	v_mul_f32_e32 v20, v20, v20
	v_fmac_f32_e32 v20, v19, v19
	v_add_f32_e32 v18, v18, v20
	ds_bpermute_b32 v19, v126, v18
	global_store_dwordx4 v[60:61], v[30:33], off
	global_store_dwordx4 v[60:61], v[22:25], off offset:256
	s_waitcnt lgkmcnt(0)
	v_add_f32_e32 v18, v18, v19
	ds_bpermute_b32 v19, v127, v18
	s_and_saveexec_b64 s[46:47], s[40:41]
	s_cbranch_execz .LBB0_118
	s_waitcnt lgkmcnt(0)
	v_add_f32_e32 v20, v18, v19
	v_lshlrev_b64 v[18:19], 6, v[58:59]
	v_lshl_add_u64 v[18:19], s[10:11], 0, v[18:19]
	v_lshl_add_u64 v[18:19], s[6:7], 2, v[18:19]
	s_lshl_b32 s18, s83, 2
	v_lshl_add_u64 v[18:19], v[18:19], 0, s[18:19]
	global_store_dword v[18:19], v20, off
; __device__ __forceinline__ unsigned pk2(float lo, float hi) { unsigned r; asm("v_cvt_pk_bf16_f32 %0, %1, %2" : "=v"(r) : "v"(lo), "v"(hi)); return r; }
; __device__ __forceinline__ float bf_lo(unsigned w) { return __uint_as_float(w << 16); }
; __device__ __forceinline__ float bf_hi(unsigned w) { return __uint_as_float(w & 0xffff0000u); }
; #define PG8_WAIT_V(n) asm volatile("s_waitcnt vmcnt(" #n ")" ::: "memory")
; #define PG8_BAR __builtin_amdgcn_s_barrier()
;     __device__ __forceinline__ void operator()(const f32x4 (&acc)[2][2][4][2], const Unit& u, int  , int wr, int wc, int fr, int fq) const {
;     ...
;             for (int bj = 0; bj < 2; ++bj) {
;                 const u32x4 r = rv[g & 1][bj]; const f32x4 a0 = acc[ai][bj][m][0], a1 = acc[ai][bj][m][1];
;                 u32x4 o; o.x = pk2(bf_lo(r.x) + a0[0], bf_hi(r.x) + a0[1]); o.y = pk2(bf_lo(r.y) + a0[2], bf_hi(r.y) + a0[3]);
;                 o.z = pk2(bf_lo(r.z) + a1[0], bf_hi(r.z) + a1[1]); o.w = pk2(bf_lo(r.w) + a1[2], bf_hi(r.w) + a1[3]);
;                 *(u32x4*)(hb + off + bj * HALF) = o;
; #pragma unroll
;                 for (int e = 0; e < 4; ++e) { const float x0 = bf_lo(o[e]), x1 = bf_hi(o[e]); s += x0 * x0 + x1 * x1; }
;             }
;             s += __shfl_xor(s, 16); s += __shfl_xor(s, 32);
;             if (fq == 0) ssq[(size_t)row * 16 + u.pn * 4 + wc] = s;
; template <class Epi>
; __device__ __forceinline__ void gemm_phase(LAS unsigned char* lds, const Gemm g, const StaticOrder& S, const Epi& E) {
;     ...
;     PG8_WAIT_V(0);
;     if (wr == 0) PG8_BAR;
;     PG8_BAR;
.LBB0_118:
	s_or_b64 exec, exec, s[46:47]
	s_waitcnt vmcnt(15)
	v_lshlrev_b32_e32 v18, 16, v194
	v_add_f32_e32 v14, v14, v18
	v_and_b32_e32 v18, 0xffff0000, v194
	v_add_f32_e32 v15, v15, v18
	v_cvt_pk_bf16_f32 v14, v14, v15
	v_lshlrev_b32_e32 v15, 16, v195
	v_add_f32_e32 v15, v16, v15
	v_and_b32_e32 v16, 0xffff0000, v195
	v_add_f32_e32 v16, v17, v16
	v_cvt_pk_bf16_f32 v15, v15, v16
	v_lshlrev_b32_e32 v16, 16, v196
	v_add_f32_e32 v10, v10, v16
	v_and_b32_e32 v16, 0xffff0000, v196
	v_add_f32_e32 v11, v11, v16
	v_cvt_pk_bf16_f32 v16, v10, v11
	v_and_b32_e32 v11, 0xffff0000, v197
	v_lshlrev_b32_e32 v10, 16, v197
	v_add_f32_e32 v11, v13, v11
	v_add_f32_e32 v10, v12, v10
	v_cvt_pk_bf16_f32 v17, v10, v11
	v_and_b32_e32 v11, 0xffff0000, v14
	v_lshlrev_b32_e32 v10, 16, v14
	v_mul_f32_e32 v11, v11, v11
	v_and_b32_e32 v12, 0xffff0000, v15
	v_fmac_f32_e32 v11, v10, v10
	v_lshlrev_b32_e32 v10, 16, v15
	v_mul_f32_e32 v12, v12, v12
	v_fmac_f32_e32 v12, v10, v10
	v_add_f32_e32 v10, v11, v12
	v_and_b32_e32 v12, 0xffff0000, v16
	v_lshlrev_b32_e32 v11, 16, v16
	v_mul_f32_e32 v12, v12, v12
	v_fmac_f32_e32 v12, v11, v11
	v_add_f32_e32 v10, v10, v12
	v_and_b32_e32 v12, 0xffff0000, v17
	v_lshlrev_b32_e32 v11, 16, v17
	v_mul_f32_e32 v12, v12, v12
	v_fmac_f32_e32 v12, v11, v11
	s_waitcnt vmcnt(14)
	v_lshlrev_b32_e32 v11, 16, v198
	v_add_f32_e32 v6, v6, v11
	v_and_b32_e32 v11, 0xffff0000, v198
	v_add_f32_e32 v7, v7, v11
	v_cvt_pk_bf16_f32 v6, v6, v7
	v_lshlrev_b32_e32 v7, 16, v199
	v_add_f32_e32 v7, v8, v7
	v_and_b32_e32 v8, 0xffff0000, v199
	v_add_f32_e32 v8, v9, v8
	v_cvt_pk_bf16_f32 v7, v7, v8
	v_lshlrev_b32_e32 v8, 16, v200
	v_add_f32_e32 v2, v2, v8
	v_and_b32_e32 v8, 0xffff0000, v200
	v_add_f32_e32 v3, v3, v8
	v_cvt_pk_bf16_f32 v8, v2, v3
	v_and_b32_e32 v3, 0xffff0000, v201
	v_lshlrev_b32_e32 v2, 16, v201
	v_add_f32_e32 v3, v5, v3
	v_add_f32_e32 v2, v4, v2
	v_cvt_pk_bf16_f32 v9, v2, v3
	v_and_b32_e32 v3, 0xffff0000, v6
	v_lshlrev_b32_e32 v2, 16, v6
	v_mul_f32_e32 v3, v3, v3
	v_add_f32_e32 v10, v10, v12
	v_fmac_f32_e32 v3, v2, v2
	v_and_b32_e32 v4, 0xffff0000, v7
	v_add_f32_e32 v2, v10, v3
	v_lshlrev_b32_e32 v3, 16, v7
	v_mul_f32_e32 v4, v4, v4
	v_fmac_f32_e32 v4, v3, v3
	v_add_f32_e32 v2, v2, v4
	v_and_b32_e32 v4, 0xffff0000, v8
	v_lshlrev_b32_e32 v3, 16, v8
	v_mul_f32_e32 v4, v4, v4
	v_fmac_f32_e32 v4, v3, v3
	v_add_f32_e32 v2, v2, v4
	v_and_b32_e32 v4, 0xffff0000, v9
	v_lshlrev_b32_e32 v3, 16, v9
	v_mul_f32_e32 v4, v4, v4
	v_fmac_f32_e32 v4, v3, v3
	v_add_f32_e32 v2, v2, v4
	ds_bpermute_b32 v3, v126, v2
	global_store_dwordx4 v[44:45], v[14:17], off
	global_store_dwordx4 v[44:45], v[6:9], off offset:256
	s_waitcnt lgkmcnt(0)
	v_add_f32_e32 v2, v2, v3
	ds_bpermute_b32 v3, v127, v2
	s_and_saveexec_b64 s[46:47], s[40:41]
	s_cbranch_execz .LBB0_95
	s_waitcnt lgkmcnt(0)
	v_add_f32_e32 v4, v2, v3
	v_lshlrev_b64 v[2:3], 6, v[42:43]
	v_lshl_add_u64 v[2:3], s[10:11], 0, v[2:3]
	v_lshl_add_u64 v[2:3], s[6:7], 2, v[2:3]
	s_lshl_b32 s18, s83, 2
	v_lshl_add_u64 v[2:3], v[2:3], 0, s[18:19]
	global_store_dword v[2:3], v4, off
	s_branch .LBB0_95
.LBB0_120:
	v_mov_b32_e32 v188, 1
	v_mov_b32_e32 v189, 0x358637bd
	v_mov_b32_e32 v190, 0x260
	v_mov_b32_e32 v191, 0x3c0881c4
	v_mov_b32_e32 v194, 0xf149f2ca
	v_mov_b32_e32 v195, 0xc0
	v_mov_b32_e32 v196, 0x70
	v_mov_b32_e32 v197, 0x71
	v_mov_b32_e32 v198, 5
	v_mov_b32_e32 v199, 2
	v_mov_b32_e32 v200, 3
	v_not_b32_e32 v201, 63
	v_not_b32_e32 v202, 31
	s_waitcnt vmcnt(0)
	s_cmpk_gt_u32 s70, 0xff
	v_readlane_b32 s70, v254, 40
	v_readlane_b32 s84, v254, 42
	v_readlane_b32 s71, v254, 41
	v_readlane_b32 s86, v254, 44
	v_readlane_b32 s87, v254, 45
	v_readlane_b32 s88, v252, 6
	v_readlane_b32 s85, v254, 43
	s_cbranch_scc1 .LBB0_122
	s_barrier
